# S5 pass-2 phase rewritten by hand too (scan from accumulators, f16 state image via LDS transposed reads, readout MFMAs ride inside the next round scan); counted vmcnt at loop tops
# speedup vs baseline: 1.0482x; 1.0343x over previous
.Lp6_top:
	s_waitcnt vmcnt(4)
.Lp6_top_body:
	v_mov_b64_e32 v[52:53], v[68:69]
	v_mov_b64_e32 v[54:55], v[70:71]
	v_mov_b64_e32 v[56:57], v[72:73]
	v_mov_b64_e32 v[58:59], v[74:75]
	v_mov_b64_e32 v[60:61], v[76:77]
	v_mov_b64_e32 v[62:63], v[78:79]
	v_mov_b64_e32 v[64:65], v[80:81]
	v_mov_b64_e32 v[66:67], v[82:83]
	s_mov_b32 s4, s5
	s_add_i32 s5, s5, s9
	s_cmpk_gt_u32 s5, 0x83f
	s_cbranch_scc1 .Lp6_compute
.Lp6_prefetch:
	s_lshr_b32 s6, s5, 4
	s_and_b32 s7, s5, 15
	s_lshl_b32 s11, s7, 2
	s_add_i32 s11, s11, s20
	s_lshl_b32 s11, s11, 5
	s_cmp_lt_u32 s6, 4
	s_mov_b32 s10, 0x80000
	s_cselect_b32 s33, s10, 0x1000000
	s_movk_i32 s10, 0x4000
	s_cselect_b32 s32, s10, 0xffffff00
	s_lshl_b32 s10, s6, 6
	s_add_i32 s32, s32, s10
	s_lshl_b32 s32, s32, 11
	s_add_i32 s32, s32, s11
	v_mul_lo_u32 v9, v2, s33
	v_add3_u32 v11, v4, v9, s32
	global_load_dwordx4 v[68:71], v11, s[54:55]
	global_load_dwordx4 v[72:75], v11, s[56:57]
	global_load_dwordx4 v[76:79], v11, s[58:59]
	global_load_dwordx4 v[80:83], v11, s[66:67]
	s_cmp_eq_u32 s35, 0
	s_cbranch_scc1 .Lp6_compute
	s_mov_b32 s35, 0
	s_waitcnt vmcnt(0)
	s_branch .Lp6_top_body

.LBB0_650:
	s_cmp_lt_i32 s90, 9
	s_cselect_b64 s[0:1], -1, 0
	s_and_b64 s[2:3], s[0:1], s[2:3]
	s_andn2_b64 vcc, exec, s[2:3]
	s_cbranch_vccnz .LBB0_659
	s_cmpk_gt_u32 s8, 0x83f
	s_cbranch_scc1 .Lp8_done
	s_and_b32 s22, s95, 1
	s_lshr_b32 s20, s95, 1
	s_add_u32 s12, s30, 0x40000
	s_addc_u32 s13, s31, 0
	s_add_u32 s14, s30, 0x60000
	s_addc_u32 s15, s31, 0
	s_add_u32 s68, s30, 0xe0000
	s_addc_u32 s69, s31, 0
	s_add_u32 s44, s30, 0x10800000
	s_addc_u32 s45, s31, 0
	s_add_u32 s74, s36, 0x2100000
	s_addc_u32 s75, s37, 0
	v_readlane_b32 s2, v240, 3
	v_readlane_b32 s3, v240, 4
	s_mul_i32 s10, s22, 3
	s_add_i32 s10, s10, 0
	s_lshl_b32 s76, s10, 10
	s_lshl_b32 s10, s10, 15
	s_add_u32 s54, s36, s10
	s_addc_u32 s55, s37, 0
	s_mul_i32 s10, s22, 1
	s_add_i32 s10, s10, 1
	s_lshl_b32 s77, s10, 10
	s_lshl_b32 s10, s10, 15
	s_add_u32 s56, s36, s10
	s_addc_u32 s57, s37, 0
	s_mul_i32 s10, s22, -1
	s_add_i32 s10, s10, 2
	s_lshl_b32 s78, s10, 10
	s_lshl_b32 s10, s10, 15
	s_add_u32 s58, s36, s10
	s_addc_u32 s59, s37, 0
	s_mul_i32 s10, s22, -3
	s_add_i32 s10, s10, 3
	s_lshl_b32 s79, s10, 10
	s_lshl_b32 s10, s10, 15
	s_add_u32 s66, s36, s10
	s_addc_u32 s67, s37, 0
	s_mov_b32 s81, 0x3a800000
	s_mov_b32 s82, 0x3d372713
	v_and_b32_e32 v0, 31, v176
	v_lshrrev_b32_e32 v1, 5, v176
	v_bfe_u32 v2, v0, 2, 1
	v_lshrrev_b32_e32 v9, 3, v0
	v_and_b32_e32 v10, 3, v0
	v_lshl_or_b32 v3, v9, 2, v10
	v_and_b32_e32 v93, 15, v176
	v_lshrrev_b32_e32 v94, 4, v176
	v_mov_b32_e32 v95, v93
	s_cmp_eq_u32 s22, 0
	s_cbranch_scc1 .Lp8_fwd
	v_sub_u32_e32 v3, 15, v3
	v_sub_u32_e32 v95, 15, v93
.Lp8_fwd:
	v_lshlrev_b32_e32 v4, 11, v3
	v_lshl_add_u32 v4, v1, 4, v4
	v_lshlrev_b32_e32 v5, 5, v0
	v_lshl_add_u32 v5, v1, 4, v5
	v_lshrrev_b32_e32 v6, 1, v0
	v_lshlrev_b32_e32 v6, 3, v6
	v_mov_b32_e32 v9, 0x420000
	v_mul_lo_u32 v7, v1, v9
	v_lshl_add_u32 v7, v0, 2, v7
	s_mul_i32 s10, s95, 0x2100
	v_lshl_add_u32 v9, v1, 7, v0
	v_lshlrev_b32_e32 v9, 4, v9
	v_add_u32_e32 v84, s10, v9
	v_lshrrev_b32_e32 v9, 2, v93
	v_lshl_add_u32 v9, v94, 3, v9
	v_lshlrev_b32_e32 v9, 4, v9
	v_and_b32_e32 v10, 1, v93
	v_lshl_add_u32 v9, v10, 3, v9
	v_bfe_u32 v10, v93, 1, 1
	v_mov_b32_e32 v85, 0x1040
	v_mul_lo_u32 v10, v10, v85
	v_add3_u32 v85, v9, v10, s10
	v_lshlrev_b32_e32 v86, 8, v93
	v_lshl_add_u32 v86, v94, 4, v86
	s_lshl_b32 s10, s95, 13
	s_add_i32 s10, s10, 0x10800
	v_lshlrev_b32_e32 v9, 6, v95
	v_lshl_add_u32 v9, v94, 4, v9
	v_add_u32_e32 v87, s10, v9
	v_lshrrev_b32_e32 v93, 7, v204
	v_bfe_u32 v94, v204, 1, 6
	v_and_b32_e32 v95, 1, v204
	v_lshlrev_b32_e32 v9, 14, v93
	v_lshl_add_u32 v9, v94, 6, v9
	v_lshl_add_u32 v9, v95, 5, v9
	v_add_u32_e32 v88, 0x10800, v9
	v_lshlrev_b32_e32 v9, 11, v94
	v_lshl_add_u32 v9, v93, 5, v9
	v_lshl_add_u32 v89, v95, 4, v9
	v_lshlrev_b32_e32 v9, 6, v93
	v_lshl_add_u32 v90, v95, 5, v9
	v_and_b32_e32 v9, 1, v0
	v_mov_b32_e32 v10, 0x80000000
	v_cmp_eq_u32_e32 vcc, 0, v9
	s_nop 3
	v_cndmask_b32_e32 v8, 0, v10, vcc
	s_mov_b32 s27, -1
	s_mov_b32 s5, s8
	s_mov_b32 s35, 1
	s_branch .Lp8_prefetch
.Lp8_top:
	s_waitcnt vmcnt(2)
.Lp8_top_body:
	v_mov_b64_e32 v[52:53], v[68:69]
	v_mov_b64_e32 v[54:55], v[70:71]
	v_mov_b64_e32 v[56:57], v[72:73]
	v_mov_b64_e32 v[58:59], v[74:75]
	v_mov_b64_e32 v[60:61], v[76:77]
	v_mov_b64_e32 v[62:63], v[78:79]
	v_mov_b64_e32 v[64:65], v[80:81]
	v_mov_b64_e32 v[66:67], v[82:83]
	v_mov_b32_e32 v12, v28
	v_mov_b32_e32 v13, v29
	v_mov_b32_e32 v14, v30
	v_mov_b32_e32 v15, v31
	s_mov_b32 s4, s5
	s_add_i32 s5, s5, s9
	s_cmpk_gt_u32 s5, 0x83f
	s_cbranch_scc1 .Lp8_compute
.Lp8_prefetch:
	s_lshr_b32 s6, s5, 4
	s_and_b32 s7, s5, 15
	s_lshl_b32 s11, s7, 2
	s_add_i32 s11, s11, s20
	s_mul_i32 s10, s22, 0x108
	s_add_i32 s10, s10, s6
	s_lshl_b32 s10, s10, 6
	s_add_i32 s10, s10, s11
	s_lshl_b32 s10, s10, 9
	s_add_u32 s40, s44, s10
	s_addc_u32 s41, s45, 0
	s_lshl_b32 s11, s11, 5
	s_cmp_lt_u32 s6, 4
	s_mov_b32 s10, 0x80000
	s_cselect_b32 s33, s10, 0x1000000
	s_movk_i32 s10, 0x4000
	s_cselect_b32 s32, s10, 0xffffff00
	s_lshl_b32 s10, s6, 6
	s_add_i32 s32, s32, s10
	s_lshl_b32 s32, s32, 11
	s_add_i32 s32, s32, s11
	v_mul_lo_u32 v9, v2, s33
	v_add3_u32 v11, v4, v9, s32
	global_load_dwordx4 v[68:71], v11, s[54:55]
	global_load_dwordx4 v[72:75], v11, s[56:57]
	global_load_dwordx4 v[76:79], v11, s[58:59]
	global_load_dwordx4 v[80:83], v11, s[66:67]
	global_load_dword v28, v7, s[40:41] offset:0
	global_load_dword v29, v7, s[40:41] offset:128
	global_load_dword v30, v7, s[40:41] offset:256
	global_load_dword v31, v7, s[40:41] offset:384
	s_cmp_eq_u32 s35, 0
	s_cbranch_scc1 .Lp8_compute
	s_mov_b32 s35, 0
	s_waitcnt vmcnt(0)
	s_branch .Lp8_top_body
.Lp8_compute:
	s_lshr_b32 s6, s4, 4
	s_and_b32 s7, s4, 15
	s_cmp_eq_u32 s7, s27
	s_cbranch_scc1 .Lp8_have_g
	s_mov_b32 s27, s7
	s_lshl_b32 s25, s7, 2
	s_add_i32 s25, s25, s20
	s_lshl_b32 s10, s25, 1
	s_add_i32 s10, s10, s22
	s_lshl_b32 s10, s10, 12
	s_add_u32 s46, s14, s10
	s_addc_u32 s47, s15, 0
	s_add_u32 s70, s68, s10
	s_addc_u32 s71, s69, 0
	s_lshl_b32 s10, s22, 6
	s_add_i32 s10, s10, s25
	s_lshl_b32 s10, s10, 9
	s_add_u32 s48, s12, s10
	s_addc_u32 s49, s13, 0
	s_lshl_b32 s10, s7, 8
	s_add_u32 s72, s2, s10
	s_addc_u32 s73, s3, 0
	global_load_dwordx4 v[36:39], v5, s[46:47] offset:0
	global_load_dwordx4 v[40:43], v5, s[46:47] offset:1024
	global_load_dwordx4 v[44:47], v5, s[46:47] offset:2048
	global_load_dwordx4 v[48:51], v5, s[46:47] offset:3072
	global_load_dwordx4 v[160:163], v86, s[70:71] offset:0
	global_load_dwordx4 v[164:167], v86, s[70:71] offset:64
	global_load_dwordx4 v[168:171], v86, s[70:71] offset:128
	global_load_dwordx4 v[172:175], v86, s[70:71] offset:192
	global_load_dwordx2 v[194:195], v6, s[48:49] offset:0
	global_load_dwordx2 v[196:197], v6, s[48:49] offset:128
	global_load_dwordx2 v[198:199], v6, s[48:49] offset:256
	global_load_dwordx2 v[200:201], v6, s[48:49] offset:384
	global_load_dwordx4 v[222:225], v90, s[72:73]
	global_load_dwordx4 v[226:229], v90, s[72:73] offset:16
	s_waitcnt vmcnt(0)
	v_mov_b32_e32 v20, v194
	v_xor_b32_e32 v24, v8, v195
	v_mov_b32_e32 v21, v196
	v_xor_b32_e32 v25, v8, v197
	v_mov_b32_e32 v22, v198
	v_xor_b32_e32 v26, v8, v199
	v_mov_b32_e32 v23, v200
	v_xor_b32_e32 v27, v8, v201
.Lp8_have_g:
	s_cmp_lt_u32 s6, 4
	s_mov_b32 s10, 0x80000
	s_cselect_b32 s84, s10, 0x1000000
	s_movk_i32 s10, 0x4000
	s_cselect_b32 s83, s10, 0xffffff00
	s_lshl_b32 s10, s6, 6
	s_add_i32 s83, s83, s10
	s_lshl_b32 s83, s83, 11
	s_lshl_b32 s10, s7, 7
	s_add_i32 s83, s83, s10
	v_add_u32_e32 v91, s83, v89
	v_add_u32_e32 v92, s84, v91
	global_load_dwordx4 v[214:217], v91, s[36:37]
	global_load_dwordx4 v[218:221], v92, s[36:37]
	v_mfma_f32_32x32x16_f16 v[96:111], v[52:55], v[36:39], 0
	v_mfma_f32_32x32x16_f16 v[112:127], v[52:55], v[40:43], 0
	v_mfma_f32_32x32x16_f16 v[128:143], v[52:55], v[44:47], 0
	v_mfma_f32_32x32x16_f16 v[144:159], v[52:55], v[48:51], 0
	s_nop 15
	v_fma_f32 v16, v20, v12, v96
	v_fma_f32 v17, v21, v13, v112
	v_fma_f32 v18, v22, v14, v128
	v_fma_f32 v19, v23, v15, v144
	v_fmac_f32_dpp v16, v12, v24 quad_perm:[1,0,3,2] row_mask:0xf bank_mask:0xf
	v_fmac_f32_dpp v17, v13, v25 quad_perm:[1,0,3,2] row_mask:0xf bank_mask:0xf
	v_fmac_f32_dpp v18, v14, v26 quad_perm:[1,0,3,2] row_mask:0xf bank_mask:0xf
	v_fmac_f32_dpp v19, v15, v27 quad_perm:[1,0,3,2] row_mask:0xf bank_mask:0xf
	v_fma_f32 v12, v20, v16, v97
	v_fma_f32 v13, v21, v17, v113
	v_fma_f32 v14, v22, v18, v129
	v_fma_f32 v15, v23, v19, v145
	v_fmac_f32_dpp v12, v16, v24 quad_perm:[1,0,3,2] row_mask:0xf bank_mask:0xf
	v_fmac_f32_dpp v13, v17, v25 quad_perm:[1,0,3,2] row_mask:0xf bank_mask:0xf
	v_fmac_f32_dpp v14, v18, v26 quad_perm:[1,0,3,2] row_mask:0xf bank_mask:0xf
	v_fmac_f32_dpp v15, v19, v27 quad_perm:[1,0,3,2] row_mask:0xf bank_mask:0xf
	v_cvt_pk_f16_f32 v178, v16, v12
	v_cvt_pk_f16_f32 v182, v17, v13
	v_cvt_pk_f16_f32 v186, v18, v14
	v_cvt_pk_f16_f32 v190, v19, v15
	v_fma_f32 v16, v20, v12, v98
	v_fma_f32 v17, v21, v13, v114
	v_fma_f32 v18, v22, v14, v130
	v_fma_f32 v19, v23, v15, v146
	v_fmac_f32_dpp v16, v12, v24 quad_perm:[1,0,3,2] row_mask:0xf bank_mask:0xf
	v_fmac_f32_dpp v17, v13, v25 quad_perm:[1,0,3,2] row_mask:0xf bank_mask:0xf
	v_fmac_f32_dpp v18, v14, v26 quad_perm:[1,0,3,2] row_mask:0xf bank_mask:0xf
	v_fmac_f32_dpp v19, v15, v27 quad_perm:[1,0,3,2] row_mask:0xf bank_mask:0xf
	v_fma_f32 v12, v20, v16, v99
	v_fma_f32 v13, v21, v17, v115
	v_fma_f32 v14, v22, v18, v131
	v_fma_f32 v15, v23, v19, v147
	v_fmac_f32_dpp v12, v16, v24 quad_perm:[1,0,3,2] row_mask:0xf bank_mask:0xf
	v_fmac_f32_dpp v13, v17, v25 quad_perm:[1,0,3,2] row_mask:0xf bank_mask:0xf
	v_fmac_f32_dpp v14, v18, v26 quad_perm:[1,0,3,2] row_mask:0xf bank_mask:0xf
	v_fmac_f32_dpp v15, v19, v27 quad_perm:[1,0,3,2] row_mask:0xf bank_mask:0xf
	v_cvt_pk_f16_f32 v179, v16, v12
	v_cvt_pk_f16_f32 v183, v17, v13
	v_cvt_pk_f16_f32 v187, v18, v14
	v_cvt_pk_f16_f32 v191, v19, v15
	v_fma_f32 v16, v20, v12, v100
	v_fma_f32 v17, v21, v13, v116
	v_fma_f32 v18, v22, v14, v132
	v_fma_f32 v19, v23, v15, v148
	v_fmac_f32_dpp v16, v12, v24 quad_perm:[1,0,3,2] row_mask:0xf bank_mask:0xf
	v_fmac_f32_dpp v17, v13, v25 quad_perm:[1,0,3,2] row_mask:0xf bank_mask:0xf
	v_fmac_f32_dpp v18, v14, v26 quad_perm:[1,0,3,2] row_mask:0xf bank_mask:0xf
	v_fmac_f32_dpp v19, v15, v27 quad_perm:[1,0,3,2] row_mask:0xf bank_mask:0xf
	v_fma_f32 v12, v20, v16, v101
	v_fma_f32 v13, v21, v17, v117
	v_fma_f32 v14, v22, v18, v133
	v_fma_f32 v15, v23, v19, v149
	v_fmac_f32_dpp v12, v16, v24 quad_perm:[1,0,3,2] row_mask:0xf bank_mask:0xf
	v_fmac_f32_dpp v13, v17, v25 quad_perm:[1,0,3,2] row_mask:0xf bank_mask:0xf
	v_fmac_f32_dpp v14, v18, v26 quad_perm:[1,0,3,2] row_mask:0xf bank_mask:0xf
	v_fmac_f32_dpp v15, v19, v27 quad_perm:[1,0,3,2] row_mask:0xf bank_mask:0xf
	v_cvt_pk_f16_f32 v180, v16, v12
	v_cvt_pk_f16_f32 v184, v17, v13
	v_cvt_pk_f16_f32 v188, v18, v14
	v_cvt_pk_f16_f32 v192, v19, v15
	v_fma_f32 v16, v20, v12, v102
	v_fma_f32 v17, v21, v13, v118
	v_fma_f32 v18, v22, v14, v134
	v_fma_f32 v19, v23, v15, v150
	v_fmac_f32_dpp v16, v12, v24 quad_perm:[1,0,3,2] row_mask:0xf bank_mask:0xf
	v_fmac_f32_dpp v17, v13, v25 quad_perm:[1,0,3,2] row_mask:0xf bank_mask:0xf
	v_fmac_f32_dpp v18, v14, v26 quad_perm:[1,0,3,2] row_mask:0xf bank_mask:0xf
	v_fmac_f32_dpp v19, v15, v27 quad_perm:[1,0,3,2] row_mask:0xf bank_mask:0xf
	v_fma_f32 v12, v20, v16, v103
	v_fma_f32 v13, v21, v17, v119
	v_fma_f32 v14, v22, v18, v135
	v_fma_f32 v15, v23, v19, v151
	v_fmac_f32_dpp v12, v16, v24 quad_perm:[1,0,3,2] row_mask:0xf bank_mask:0xf
	v_fmac_f32_dpp v13, v17, v25 quad_perm:[1,0,3,2] row_mask:0xf bank_mask:0xf
	v_fmac_f32_dpp v14, v18, v26 quad_perm:[1,0,3,2] row_mask:0xf bank_mask:0xf
	v_fmac_f32_dpp v15, v19, v27 quad_perm:[1,0,3,2] row_mask:0xf bank_mask:0xf
	v_cvt_pk_f16_f32 v181, v16, v12
	v_cvt_pk_f16_f32 v185, v17, v13
	v_cvt_pk_f16_f32 v189, v18, v14
	v_cvt_pk_f16_f32 v193, v19, v15
	ds_write_b128 v84, v[178:181] offset:0
	ds_write_b128 v84, v[182:185] offset:512
	ds_write_b128 v84, v[186:189] offset:1024
	ds_write_b128 v84, v[190:193] offset:1536
	v_fma_f32 v16, v20, v12, v104
	v_fma_f32 v17, v21, v13, v120
	v_fma_f32 v18, v22, v14, v136
	v_fma_f32 v19, v23, v15, v152
	v_fmac_f32_dpp v16, v12, v24 quad_perm:[1,0,3,2] row_mask:0xf bank_mask:0xf
	v_fmac_f32_dpp v17, v13, v25 quad_perm:[1,0,3,2] row_mask:0xf bank_mask:0xf
	v_fmac_f32_dpp v18, v14, v26 quad_perm:[1,0,3,2] row_mask:0xf bank_mask:0xf
	v_fmac_f32_dpp v19, v15, v27 quad_perm:[1,0,3,2] row_mask:0xf bank_mask:0xf
	v_fma_f32 v12, v20, v16, v105
	v_fma_f32 v13, v21, v17, v121
	v_fma_f32 v14, v22, v18, v137
	v_fma_f32 v15, v23, v19, v153
	v_fmac_f32_dpp v12, v16, v24 quad_perm:[1,0,3,2] row_mask:0xf bank_mask:0xf
	v_fmac_f32_dpp v13, v17, v25 quad_perm:[1,0,3,2] row_mask:0xf bank_mask:0xf
	v_fmac_f32_dpp v14, v18, v26 quad_perm:[1,0,3,2] row_mask:0xf bank_mask:0xf
	v_fmac_f32_dpp v15, v19, v27 quad_perm:[1,0,3,2] row_mask:0xf bank_mask:0xf
	v_cvt_pk_f16_f32 v178, v16, v12
	v_cvt_pk_f16_f32 v182, v17, v13
	v_cvt_pk_f16_f32 v186, v18, v14
	v_cvt_pk_f16_f32 v190, v19, v15
	v_fma_f32 v16, v20, v12, v106
	v_fma_f32 v17, v21, v13, v122
	v_fma_f32 v18, v22, v14, v138
	v_fma_f32 v19, v23, v15, v154
	v_fmac_f32_dpp v16, v12, v24 quad_perm:[1,0,3,2] row_mask:0xf bank_mask:0xf
	v_fmac_f32_dpp v17, v13, v25 quad_perm:[1,0,3,2] row_mask:0xf bank_mask:0xf
	v_fmac_f32_dpp v18, v14, v26 quad_perm:[1,0,3,2] row_mask:0xf bank_mask:0xf
	v_fmac_f32_dpp v19, v15, v27 quad_perm:[1,0,3,2] row_mask:0xf bank_mask:0xf
	v_fma_f32 v12, v20, v16, v107
	v_fma_f32 v13, v21, v17, v123
	v_fma_f32 v14, v22, v18, v139
	v_fma_f32 v15, v23, v19, v155
	v_fmac_f32_dpp v12, v16, v24 quad_perm:[1,0,3,2] row_mask:0xf bank_mask:0xf
	v_fmac_f32_dpp v13, v17, v25 quad_perm:[1,0,3,2] row_mask:0xf bank_mask:0xf
	v_fmac_f32_dpp v14, v18, v26 quad_perm:[1,0,3,2] row_mask:0xf bank_mask:0xf
	v_fmac_f32_dpp v15, v19, v27 quad_perm:[1,0,3,2] row_mask:0xf bank_mask:0xf
	v_cvt_pk_f16_f32 v179, v16, v12
	v_cvt_pk_f16_f32 v183, v17, v13
	v_cvt_pk_f16_f32 v187, v18, v14
	v_cvt_pk_f16_f32 v191, v19, v15
	v_fma_f32 v16, v20, v12, v108
	v_fma_f32 v17, v21, v13, v124
	v_fma_f32 v18, v22, v14, v140
	v_fma_f32 v19, v23, v15, v156
	v_fmac_f32_dpp v16, v12, v24 quad_perm:[1,0,3,2] row_mask:0xf bank_mask:0xf
	v_fmac_f32_dpp v17, v13, v25 quad_perm:[1,0,3,2] row_mask:0xf bank_mask:0xf
	v_fmac_f32_dpp v18, v14, v26 quad_perm:[1,0,3,2] row_mask:0xf bank_mask:0xf
	v_fmac_f32_dpp v19, v15, v27 quad_perm:[1,0,3,2] row_mask:0xf bank_mask:0xf
	v_fma_f32 v12, v20, v16, v109
	v_fma_f32 v13, v21, v17, v125
	v_fma_f32 v14, v22, v18, v141
	v_fma_f32 v15, v23, v19, v157
	v_fmac_f32_dpp v12, v16, v24 quad_perm:[1,0,3,2] row_mask:0xf bank_mask:0xf
	v_fmac_f32_dpp v13, v17, v25 quad_perm:[1,0,3,2] row_mask:0xf bank_mask:0xf
	v_fmac_f32_dpp v14, v18, v26 quad_perm:[1,0,3,2] row_mask:0xf bank_mask:0xf
	v_fmac_f32_dpp v15, v19, v27 quad_perm:[1,0,3,2] row_mask:0xf bank_mask:0xf
	v_cvt_pk_f16_f32 v180, v16, v12
	v_cvt_pk_f16_f32 v184, v17, v13
	v_cvt_pk_f16_f32 v188, v18, v14
	v_cvt_pk_f16_f32 v192, v19, v15
	v_fma_f32 v16, v20, v12, v110
	v_fma_f32 v17, v21, v13, v126
	v_fma_f32 v18, v22, v14, v142
	v_fma_f32 v19, v23, v15, v158
	v_fmac_f32_dpp v16, v12, v24 quad_perm:[1,0,3,2] row_mask:0xf bank_mask:0xf
	v_fmac_f32_dpp v17, v13, v25 quad_perm:[1,0,3,2] row_mask:0xf bank_mask:0xf
	v_fmac_f32_dpp v18, v14, v26 quad_perm:[1,0,3,2] row_mask:0xf bank_mask:0xf
	v_fmac_f32_dpp v19, v15, v27 quad_perm:[1,0,3,2] row_mask:0xf bank_mask:0xf
	v_fma_f32 v12, v20, v16, v111
	v_fma_f32 v13, v21, v17, v127
	v_fma_f32 v14, v22, v18, v143
	v_fma_f32 v15, v23, v19, v159
	v_fmac_f32_dpp v12, v16, v24 quad_perm:[1,0,3,2] row_mask:0xf bank_mask:0xf
	v_fmac_f32_dpp v13, v17, v25 quad_perm:[1,0,3,2] row_mask:0xf bank_mask:0xf
	v_fmac_f32_dpp v14, v18, v26 quad_perm:[1,0,3,2] row_mask:0xf bank_mask:0xf
	v_fmac_f32_dpp v15, v19, v27 quad_perm:[1,0,3,2] row_mask:0xf bank_mask:0xf
	v_cvt_pk_f16_f32 v181, v16, v12
	v_cvt_pk_f16_f32 v185, v17, v13
	v_cvt_pk_f16_f32 v189, v18, v14
	v_cvt_pk_f16_f32 v193, v19, v15
	ds_write_b128 v84, v[178:181] offset:4160
	ds_write_b128 v84, v[182:185] offset:4672
	ds_write_b128 v84, v[186:189] offset:5184
	ds_write_b128 v84, v[190:193] offset:5696
	v_mfma_f32_32x32x16_f16 v[96:111], v[56:59], v[36:39], 0
	v_mfma_f32_32x32x16_f16 v[112:127], v[56:59], v[40:43], 0
	v_mfma_f32_32x32x16_f16 v[128:143], v[56:59], v[44:47], 0
	v_mfma_f32_32x32x16_f16 v[144:159], v[56:59], v[48:51], 0
	v_add_u32_e32 v93, s76, v87
	ds_read_b64_tr_b16 v[194:195], v85 offset:0
	ds_read_b64_tr_b16 v[196:197], v85 offset:64
	ds_read_b64_tr_b16 v[198:199], v85 offset:512
	ds_read_b64_tr_b16 v[200:201], v85 offset:576
	ds_read_b64_tr_b16 v[206:207], v85 offset:1024
	ds_read_b64_tr_b16 v[208:209], v85 offset:1088
	ds_read_b64_tr_b16 v[210:211], v85 offset:1536
	ds_read_b64_tr_b16 v[212:213], v85 offset:1600
	s_nop 3
	v_fma_f32 v16, v20, v12, v96
	v_fma_f32 v17, v21, v13, v112
	v_fma_f32 v18, v22, v14, v128
	v_fma_f32 v19, v23, v15, v144
	v_fmac_f32_dpp v16, v12, v24 quad_perm:[1,0,3,2] row_mask:0xf bank_mask:0xf
	v_fmac_f32_dpp v17, v13, v25 quad_perm:[1,0,3,2] row_mask:0xf bank_mask:0xf
	v_fmac_f32_dpp v18, v14, v26 quad_perm:[1,0,3,2] row_mask:0xf bank_mask:0xf
	v_fmac_f32_dpp v19, v15, v27 quad_perm:[1,0,3,2] row_mask:0xf bank_mask:0xf
	v_fma_f32 v12, v20, v16, v97
	v_fma_f32 v13, v21, v17, v113
	v_fma_f32 v14, v22, v18, v129
	v_fma_f32 v15, v23, v19, v145
	v_fmac_f32_dpp v12, v16, v24 quad_perm:[1,0,3,2] row_mask:0xf bank_mask:0xf
	v_fmac_f32_dpp v13, v17, v25 quad_perm:[1,0,3,2] row_mask:0xf bank_mask:0xf
	v_fmac_f32_dpp v14, v18, v26 quad_perm:[1,0,3,2] row_mask:0xf bank_mask:0xf
	v_fmac_f32_dpp v15, v19, v27 quad_perm:[1,0,3,2] row_mask:0xf bank_mask:0xf
	v_cvt_pk_f16_f32 v178, v16, v12
	v_cvt_pk_f16_f32 v182, v17, v13
	v_cvt_pk_f16_f32 v186, v18, v14
	v_cvt_pk_f16_f32 v190, v19, v15
	s_waitcnt lgkmcnt(6)
	v_mfma_f32_16x16x32_f16 v[32:35], v[160:163], v[194:197], 0
	s_waitcnt lgkmcnt(4)
	v_mfma_f32_16x16x32_f16 v[32:35], v[164:167], v[198:201], v[32:35]
	s_waitcnt lgkmcnt(2)
	v_mfma_f32_16x16x32_f16 v[32:35], v[168:171], v[206:209], v[32:35]
	s_waitcnt lgkmcnt(0)
	v_mfma_f32_16x16x32_f16 v[32:35], v[172:175], v[210:213], v[32:35]
	v_fma_f32 v16, v20, v12, v98
	v_fma_f32 v17, v21, v13, v114
	v_fma_f32 v18, v22, v14, v130
	v_fma_f32 v19, v23, v15, v146
	v_fmac_f32_dpp v16, v12, v24 quad_perm:[1,0,3,2] row_mask:0xf bank_mask:0xf
	v_fmac_f32_dpp v17, v13, v25 quad_perm:[1,0,3,2] row_mask:0xf bank_mask:0xf
	v_fmac_f32_dpp v18, v14, v26 quad_perm:[1,0,3,2] row_mask:0xf bank_mask:0xf
	v_fmac_f32_dpp v19, v15, v27 quad_perm:[1,0,3,2] row_mask:0xf bank_mask:0xf
	v_fma_f32 v12, v20, v16, v99
	v_fma_f32 v13, v21, v17, v115
	v_fma_f32 v14, v22, v18, v131
	v_fma_f32 v15, v23, v19, v147
	v_fmac_f32_dpp v12, v16, v24 quad_perm:[1,0,3,2] row_mask:0xf bank_mask:0xf
	v_fmac_f32_dpp v13, v17, v25 quad_perm:[1,0,3,2] row_mask:0xf bank_mask:0xf
	v_fmac_f32_dpp v14, v18, v26 quad_perm:[1,0,3,2] row_mask:0xf bank_mask:0xf
	v_fmac_f32_dpp v15, v19, v27 quad_perm:[1,0,3,2] row_mask:0xf bank_mask:0xf
	v_cvt_pk_f16_f32 v179, v16, v12
	v_cvt_pk_f16_f32 v183, v17, v13
	v_cvt_pk_f16_f32 v187, v18, v14
	v_cvt_pk_f16_f32 v191, v19, v15
	ds_write_b128 v93, v[32:35] offset:0
	ds_read_b64_tr_b16 v[194:195], v85 offset:2048
	ds_read_b64_tr_b16 v[196:197], v85 offset:2112
	ds_read_b64_tr_b16 v[198:199], v85 offset:2560
	ds_read_b64_tr_b16 v[200:201], v85 offset:2624
	ds_read_b64_tr_b16 v[206:207], v85 offset:3072
	ds_read_b64_tr_b16 v[208:209], v85 offset:3136
	ds_read_b64_tr_b16 v[210:211], v85 offset:3584
	ds_read_b64_tr_b16 v[212:213], v85 offset:3648
	v_fma_f32 v16, v20, v12, v100
	v_fma_f32 v17, v21, v13, v116
	v_fma_f32 v18, v22, v14, v132
	v_fma_f32 v19, v23, v15, v148
	v_fmac_f32_dpp v16, v12, v24 quad_perm:[1,0,3,2] row_mask:0xf bank_mask:0xf
	v_fmac_f32_dpp v17, v13, v25 quad_perm:[1,0,3,2] row_mask:0xf bank_mask:0xf
	v_fmac_f32_dpp v18, v14, v26 quad_perm:[1,0,3,2] row_mask:0xf bank_mask:0xf
	v_fmac_f32_dpp v19, v15, v27 quad_perm:[1,0,3,2] row_mask:0xf bank_mask:0xf
	v_fma_f32 v12, v20, v16, v101
	v_fma_f32 v13, v21, v17, v117
	v_fma_f32 v14, v22, v18, v133
	v_fma_f32 v15, v23, v19, v149
	v_fmac_f32_dpp v12, v16, v24 quad_perm:[1,0,3,2] row_mask:0xf bank_mask:0xf
	v_fmac_f32_dpp v13, v17, v25 quad_perm:[1,0,3,2] row_mask:0xf bank_mask:0xf
	v_fmac_f32_dpp v14, v18, v26 quad_perm:[1,0,3,2] row_mask:0xf bank_mask:0xf
	v_fmac_f32_dpp v15, v19, v27 quad_perm:[1,0,3,2] row_mask:0xf bank_mask:0xf
	v_cvt_pk_f16_f32 v180, v16, v12
	v_cvt_pk_f16_f32 v184, v17, v13
	v_cvt_pk_f16_f32 v188, v18, v14
	v_cvt_pk_f16_f32 v192, v19, v15
	s_waitcnt lgkmcnt(6)
	v_mfma_f32_16x16x32_f16 v[32:35], v[160:163], v[194:197], 0
	s_waitcnt lgkmcnt(4)
	v_mfma_f32_16x16x32_f16 v[32:35], v[164:167], v[198:201], v[32:35]
	s_waitcnt lgkmcnt(2)
	v_mfma_f32_16x16x32_f16 v[32:35], v[168:171], v[206:209], v[32:35]
	s_waitcnt lgkmcnt(0)
	v_mfma_f32_16x16x32_f16 v[32:35], v[172:175], v[210:213], v[32:35]
	v_fma_f32 v16, v20, v12, v102
	v_fma_f32 v17, v21, v13, v118
	v_fma_f32 v18, v22, v14, v134
	v_fma_f32 v19, v23, v15, v150
	v_fmac_f32_dpp v16, v12, v24 quad_perm:[1,0,3,2] row_mask:0xf bank_mask:0xf
	v_fmac_f32_dpp v17, v13, v25 quad_perm:[1,0,3,2] row_mask:0xf bank_mask:0xf
	v_fmac_f32_dpp v18, v14, v26 quad_perm:[1,0,3,2] row_mask:0xf bank_mask:0xf
	v_fmac_f32_dpp v19, v15, v27 quad_perm:[1,0,3,2] row_mask:0xf bank_mask:0xf
	v_fma_f32 v12, v20, v16, v103
	v_fma_f32 v13, v21, v17, v119
	v_fma_f32 v14, v22, v18, v135
	v_fma_f32 v15, v23, v19, v151
	v_fmac_f32_dpp v12, v16, v24 quad_perm:[1,0,3,2] row_mask:0xf bank_mask:0xf
	v_fmac_f32_dpp v13, v17, v25 quad_perm:[1,0,3,2] row_mask:0xf bank_mask:0xf
	v_fmac_f32_dpp v14, v18, v26 quad_perm:[1,0,3,2] row_mask:0xf bank_mask:0xf
	v_fmac_f32_dpp v15, v19, v27 quad_perm:[1,0,3,2] row_mask:0xf bank_mask:0xf
	v_cvt_pk_f16_f32 v181, v16, v12
	v_cvt_pk_f16_f32 v185, v17, v13
	v_cvt_pk_f16_f32 v189, v18, v14
	v_cvt_pk_f16_f32 v193, v19, v15
	ds_write_b128 v84, v[178:181] offset:0
	ds_write_b128 v84, v[182:185] offset:512
	ds_write_b128 v84, v[186:189] offset:1024
	ds_write_b128 v84, v[190:193] offset:1536
	v_fma_f32 v16, v20, v12, v104
	v_fma_f32 v17, v21, v13, v120
	v_fma_f32 v18, v22, v14, v136
	v_fma_f32 v19, v23, v15, v152
	v_fmac_f32_dpp v16, v12, v24 quad_perm:[1,0,3,2] row_mask:0xf bank_mask:0xf
	v_fmac_f32_dpp v17, v13, v25 quad_perm:[1,0,3,2] row_mask:0xf bank_mask:0xf
	v_fmac_f32_dpp v18, v14, v26 quad_perm:[1,0,3,2] row_mask:0xf bank_mask:0xf
	v_fmac_f32_dpp v19, v15, v27 quad_perm:[1,0,3,2] row_mask:0xf bank_mask:0xf
	ds_write_b128 v93, v[32:35] offset:4096
	v_fma_f32 v12, v20, v16, v105
	v_fma_f32 v13, v21, v17, v121
	v_fma_f32 v14, v22, v18, v137
	v_fma_f32 v15, v23, v19, v153
	v_fmac_f32_dpp v12, v16, v24 quad_perm:[1,0,3,2] row_mask:0xf bank_mask:0xf
	v_fmac_f32_dpp v13, v17, v25 quad_perm:[1,0,3,2] row_mask:0xf bank_mask:0xf
	v_fmac_f32_dpp v14, v18, v26 quad_perm:[1,0,3,2] row_mask:0xf bank_mask:0xf
	v_fmac_f32_dpp v15, v19, v27 quad_perm:[1,0,3,2] row_mask:0xf bank_mask:0xf
	v_cvt_pk_f16_f32 v178, v16, v12
	v_cvt_pk_f16_f32 v182, v17, v13
	v_cvt_pk_f16_f32 v186, v18, v14
	v_cvt_pk_f16_f32 v190, v19, v15
	v_fma_f32 v16, v20, v12, v106
	v_fma_f32 v17, v21, v13, v122
	v_fma_f32 v18, v22, v14, v138
	v_fma_f32 v19, v23, v15, v154
	v_fmac_f32_dpp v16, v12, v24 quad_perm:[1,0,3,2] row_mask:0xf bank_mask:0xf
	v_fmac_f32_dpp v17, v13, v25 quad_perm:[1,0,3,2] row_mask:0xf bank_mask:0xf
	v_fmac_f32_dpp v18, v14, v26 quad_perm:[1,0,3,2] row_mask:0xf bank_mask:0xf
	v_fmac_f32_dpp v19, v15, v27 quad_perm:[1,0,3,2] row_mask:0xf bank_mask:0xf
	v_fma_f32 v12, v20, v16, v107
	v_fma_f32 v13, v21, v17, v123
	v_fma_f32 v14, v22, v18, v139
	v_fma_f32 v15, v23, v19, v155
	v_fmac_f32_dpp v12, v16, v24 quad_perm:[1,0,3,2] row_mask:0xf bank_mask:0xf
	v_fmac_f32_dpp v13, v17, v25 quad_perm:[1,0,3,2] row_mask:0xf bank_mask:0xf
	v_fmac_f32_dpp v14, v18, v26 quad_perm:[1,0,3,2] row_mask:0xf bank_mask:0xf
	v_fmac_f32_dpp v15, v19, v27 quad_perm:[1,0,3,2] row_mask:0xf bank_mask:0xf
	v_cvt_pk_f16_f32 v179, v16, v12
	v_cvt_pk_f16_f32 v183, v17, v13
	v_cvt_pk_f16_f32 v187, v18, v14
	v_cvt_pk_f16_f32 v191, v19, v15
	v_fma_f32 v16, v20, v12, v108
	v_fma_f32 v17, v21, v13, v124
	v_fma_f32 v18, v22, v14, v140
	v_fma_f32 v19, v23, v15, v156
	v_fmac_f32_dpp v16, v12, v24 quad_perm:[1,0,3,2] row_mask:0xf bank_mask:0xf
	v_fmac_f32_dpp v17, v13, v25 quad_perm:[1,0,3,2] row_mask:0xf bank_mask:0xf
	v_fmac_f32_dpp v18, v14, v26 quad_perm:[1,0,3,2] row_mask:0xf bank_mask:0xf
	v_fmac_f32_dpp v19, v15, v27 quad_perm:[1,0,3,2] row_mask:0xf bank_mask:0xf
	v_fma_f32 v12, v20, v16, v109
	v_fma_f32 v13, v21, v17, v125
	v_fma_f32 v14, v22, v18, v141
	v_fma_f32 v15, v23, v19, v157
	v_fmac_f32_dpp v12, v16, v24 quad_perm:[1,0,3,2] row_mask:0xf bank_mask:0xf
	v_fmac_f32_dpp v13, v17, v25 quad_perm:[1,0,3,2] row_mask:0xf bank_mask:0xf
	v_fmac_f32_dpp v14, v18, v26 quad_perm:[1,0,3,2] row_mask:0xf bank_mask:0xf
	v_fmac_f32_dpp v15, v19, v27 quad_perm:[1,0,3,2] row_mask:0xf bank_mask:0xf
	v_cvt_pk_f16_f32 v180, v16, v12
	v_cvt_pk_f16_f32 v184, v17, v13
	v_cvt_pk_f16_f32 v188, v18, v14
	v_cvt_pk_f16_f32 v192, v19, v15
	v_fma_f32 v16, v20, v12, v110
	v_fma_f32 v17, v21, v13, v126
	v_fma_f32 v18, v22, v14, v142
	v_fma_f32 v19, v23, v15, v158
	v_fmac_f32_dpp v16, v12, v24 quad_perm:[1,0,3,2] row_mask:0xf bank_mask:0xf
	v_fmac_f32_dpp v17, v13, v25 quad_perm:[1,0,3,2] row_mask:0xf bank_mask:0xf
	v_fmac_f32_dpp v18, v14, v26 quad_perm:[1,0,3,2] row_mask:0xf bank_mask:0xf
	v_fmac_f32_dpp v19, v15, v27 quad_perm:[1,0,3,2] row_mask:0xf bank_mask:0xf
	v_fma_f32 v12, v20, v16, v111
	v_fma_f32 v13, v21, v17, v127
	v_fma_f32 v14, v22, v18, v143
	v_fma_f32 v15, v23, v19, v159
	v_fmac_f32_dpp v12, v16, v24 quad_perm:[1,0,3,2] row_mask:0xf bank_mask:0xf
	v_fmac_f32_dpp v13, v17, v25 quad_perm:[1,0,3,2] row_mask:0xf bank_mask:0xf
	v_fmac_f32_dpp v14, v18, v26 quad_perm:[1,0,3,2] row_mask:0xf bank_mask:0xf
	v_fmac_f32_dpp v15, v19, v27 quad_perm:[1,0,3,2] row_mask:0xf bank_mask:0xf
	v_cvt_pk_f16_f32 v181, v16, v12
	v_cvt_pk_f16_f32 v185, v17, v13
	v_cvt_pk_f16_f32 v189, v18, v14
	v_cvt_pk_f16_f32 v193, v19, v15
	ds_write_b128 v84, v[178:181] offset:4160
	ds_write_b128 v84, v[182:185] offset:4672
	ds_write_b128 v84, v[186:189] offset:5184
	ds_write_b128 v84, v[190:193] offset:5696
	v_mfma_f32_32x32x16_f16 v[96:111], v[60:63], v[36:39], 0
	v_mfma_f32_32x32x16_f16 v[112:127], v[60:63], v[40:43], 0
	v_mfma_f32_32x32x16_f16 v[128:143], v[60:63], v[44:47], 0
	v_mfma_f32_32x32x16_f16 v[144:159], v[60:63], v[48:51], 0
	v_add_u32_e32 v93, s77, v87
	ds_read_b64_tr_b16 v[194:195], v85 offset:0
	ds_read_b64_tr_b16 v[196:197], v85 offset:64
	ds_read_b64_tr_b16 v[198:199], v85 offset:512
	ds_read_b64_tr_b16 v[200:201], v85 offset:576
	ds_read_b64_tr_b16 v[206:207], v85 offset:1024
	ds_read_b64_tr_b16 v[208:209], v85 offset:1088
	ds_read_b64_tr_b16 v[210:211], v85 offset:1536
	ds_read_b64_tr_b16 v[212:213], v85 offset:1600
	s_nop 3
	v_fma_f32 v16, v20, v12, v96
	v_fma_f32 v17, v21, v13, v112
	v_fma_f32 v18, v22, v14, v128
	v_fma_f32 v19, v23, v15, v144
	v_fmac_f32_dpp v16, v12, v24 quad_perm:[1,0,3,2] row_mask:0xf bank_mask:0xf
	v_fmac_f32_dpp v17, v13, v25 quad_perm:[1,0,3,2] row_mask:0xf bank_mask:0xf
	v_fmac_f32_dpp v18, v14, v26 quad_perm:[1,0,3,2] row_mask:0xf bank_mask:0xf
	v_fmac_f32_dpp v19, v15, v27 quad_perm:[1,0,3,2] row_mask:0xf bank_mask:0xf
	v_fma_f32 v12, v20, v16, v97
	v_fma_f32 v13, v21, v17, v113
	v_fma_f32 v14, v22, v18, v129
	v_fma_f32 v15, v23, v19, v145
	v_fmac_f32_dpp v12, v16, v24 quad_perm:[1,0,3,2] row_mask:0xf bank_mask:0xf
	v_fmac_f32_dpp v13, v17, v25 quad_perm:[1,0,3,2] row_mask:0xf bank_mask:0xf
	v_fmac_f32_dpp v14, v18, v26 quad_perm:[1,0,3,2] row_mask:0xf bank_mask:0xf
	v_fmac_f32_dpp v15, v19, v27 quad_perm:[1,0,3,2] row_mask:0xf bank_mask:0xf
	v_cvt_pk_f16_f32 v178, v16, v12
	v_cvt_pk_f16_f32 v182, v17, v13
	v_cvt_pk_f16_f32 v186, v18, v14
	v_cvt_pk_f16_f32 v190, v19, v15
	s_waitcnt lgkmcnt(6)
	v_mfma_f32_16x16x32_f16 v[32:35], v[160:163], v[194:197], 0
	s_waitcnt lgkmcnt(4)
	v_mfma_f32_16x16x32_f16 v[32:35], v[164:167], v[198:201], v[32:35]
	s_waitcnt lgkmcnt(2)
	v_mfma_f32_16x16x32_f16 v[32:35], v[168:171], v[206:209], v[32:35]
	s_waitcnt lgkmcnt(0)
	v_mfma_f32_16x16x32_f16 v[32:35], v[172:175], v[210:213], v[32:35]
	v_fma_f32 v16, v20, v12, v98
	v_fma_f32 v17, v21, v13, v114
	v_fma_f32 v18, v22, v14, v130
	v_fma_f32 v19, v23, v15, v146
	v_fmac_f32_dpp v16, v12, v24 quad_perm:[1,0,3,2] row_mask:0xf bank_mask:0xf
	v_fmac_f32_dpp v17, v13, v25 quad_perm:[1,0,3,2] row_mask:0xf bank_mask:0xf
	v_fmac_f32_dpp v18, v14, v26 quad_perm:[1,0,3,2] row_mask:0xf bank_mask:0xf
	v_fmac_f32_dpp v19, v15, v27 quad_perm:[1,0,3,2] row_mask:0xf bank_mask:0xf
	v_fma_f32 v12, v20, v16, v99
	v_fma_f32 v13, v21, v17, v115
	v_fma_f32 v14, v22, v18, v131
	v_fma_f32 v15, v23, v19, v147
	v_fmac_f32_dpp v12, v16, v24 quad_perm:[1,0,3,2] row_mask:0xf bank_mask:0xf
	v_fmac_f32_dpp v13, v17, v25 quad_perm:[1,0,3,2] row_mask:0xf bank_mask:0xf
	v_fmac_f32_dpp v14, v18, v26 quad_perm:[1,0,3,2] row_mask:0xf bank_mask:0xf
	v_fmac_f32_dpp v15, v19, v27 quad_perm:[1,0,3,2] row_mask:0xf bank_mask:0xf
	v_cvt_pk_f16_f32 v179, v16, v12
	v_cvt_pk_f16_f32 v183, v17, v13
	v_cvt_pk_f16_f32 v187, v18, v14
	v_cvt_pk_f16_f32 v191, v19, v15
	ds_write_b128 v93, v[32:35] offset:0
	ds_read_b64_tr_b16 v[194:195], v85 offset:2048
	ds_read_b64_tr_b16 v[196:197], v85 offset:2112
	ds_read_b64_tr_b16 v[198:199], v85 offset:2560
	ds_read_b64_tr_b16 v[200:201], v85 offset:2624
	ds_read_b64_tr_b16 v[206:207], v85 offset:3072
	ds_read_b64_tr_b16 v[208:209], v85 offset:3136
	ds_read_b64_tr_b16 v[210:211], v85 offset:3584
	ds_read_b64_tr_b16 v[212:213], v85 offset:3648
	v_fma_f32 v16, v20, v12, v100
	v_fma_f32 v17, v21, v13, v116
	v_fma_f32 v18, v22, v14, v132
	v_fma_f32 v19, v23, v15, v148
	v_fmac_f32_dpp v16, v12, v24 quad_perm:[1,0,3,2] row_mask:0xf bank_mask:0xf
	v_fmac_f32_dpp v17, v13, v25 quad_perm:[1,0,3,2] row_mask:0xf bank_mask:0xf
	v_fmac_f32_dpp v18, v14, v26 quad_perm:[1,0,3,2] row_mask:0xf bank_mask:0xf
	v_fmac_f32_dpp v19, v15, v27 quad_perm:[1,0,3,2] row_mask:0xf bank_mask:0xf
	v_fma_f32 v12, v20, v16, v101
	v_fma_f32 v13, v21, v17, v117
	v_fma_f32 v14, v22, v18, v133
	v_fma_f32 v15, v23, v19, v149
	v_fmac_f32_dpp v12, v16, v24 quad_perm:[1,0,3,2] row_mask:0xf bank_mask:0xf
	v_fmac_f32_dpp v13, v17, v25 quad_perm:[1,0,3,2] row_mask:0xf bank_mask:0xf
	v_fmac_f32_dpp v14, v18, v26 quad_perm:[1,0,3,2] row_mask:0xf bank_mask:0xf
	v_fmac_f32_dpp v15, v19, v27 quad_perm:[1,0,3,2] row_mask:0xf bank_mask:0xf
	v_cvt_pk_f16_f32 v180, v16, v12
	v_cvt_pk_f16_f32 v184, v17, v13
	v_cvt_pk_f16_f32 v188, v18, v14
	v_cvt_pk_f16_f32 v192, v19, v15
	s_waitcnt lgkmcnt(6)
	v_mfma_f32_16x16x32_f16 v[32:35], v[160:163], v[194:197], 0
	s_waitcnt lgkmcnt(4)
	v_mfma_f32_16x16x32_f16 v[32:35], v[164:167], v[198:201], v[32:35]
	s_waitcnt lgkmcnt(2)
	v_mfma_f32_16x16x32_f16 v[32:35], v[168:171], v[206:209], v[32:35]
	s_waitcnt lgkmcnt(0)
	v_mfma_f32_16x16x32_f16 v[32:35], v[172:175], v[210:213], v[32:35]
	v_fma_f32 v16, v20, v12, v102
	v_fma_f32 v17, v21, v13, v118
	v_fma_f32 v18, v22, v14, v134
	v_fma_f32 v19, v23, v15, v150
	v_fmac_f32_dpp v16, v12, v24 quad_perm:[1,0,3,2] row_mask:0xf bank_mask:0xf
	v_fmac_f32_dpp v17, v13, v25 quad_perm:[1,0,3,2] row_mask:0xf bank_mask:0xf
	v_fmac_f32_dpp v18, v14, v26 quad_perm:[1,0,3,2] row_mask:0xf bank_mask:0xf
	v_fmac_f32_dpp v19, v15, v27 quad_perm:[1,0,3,2] row_mask:0xf bank_mask:0xf
	v_fma_f32 v12, v20, v16, v103
	v_fma_f32 v13, v21, v17, v119
	v_fma_f32 v14, v22, v18, v135
	v_fma_f32 v15, v23, v19, v151
	v_fmac_f32_dpp v12, v16, v24 quad_perm:[1,0,3,2] row_mask:0xf bank_mask:0xf
	v_fmac_f32_dpp v13, v17, v25 quad_perm:[1,0,3,2] row_mask:0xf bank_mask:0xf
	v_fmac_f32_dpp v14, v18, v26 quad_perm:[1,0,3,2] row_mask:0xf bank_mask:0xf
	v_fmac_f32_dpp v15, v19, v27 quad_perm:[1,0,3,2] row_mask:0xf bank_mask:0xf
	v_cvt_pk_f16_f32 v181, v16, v12
	v_cvt_pk_f16_f32 v185, v17, v13
	v_cvt_pk_f16_f32 v189, v18, v14
	v_cvt_pk_f16_f32 v193, v19, v15
	ds_write_b128 v84, v[178:181] offset:0
	ds_write_b128 v84, v[182:185] offset:512
	ds_write_b128 v84, v[186:189] offset:1024
	ds_write_b128 v84, v[190:193] offset:1536
	v_fma_f32 v16, v20, v12, v104
	v_fma_f32 v17, v21, v13, v120
	v_fma_f32 v18, v22, v14, v136
	v_fma_f32 v19, v23, v15, v152
	v_fmac_f32_dpp v16, v12, v24 quad_perm:[1,0,3,2] row_mask:0xf bank_mask:0xf
	v_fmac_f32_dpp v17, v13, v25 quad_perm:[1,0,3,2] row_mask:0xf bank_mask:0xf
	v_fmac_f32_dpp v18, v14, v26 quad_perm:[1,0,3,2] row_mask:0xf bank_mask:0xf
	v_fmac_f32_dpp v19, v15, v27 quad_perm:[1,0,3,2] row_mask:0xf bank_mask:0xf
	ds_write_b128 v93, v[32:35] offset:4096
	v_fma_f32 v12, v20, v16, v105
	v_fma_f32 v13, v21, v17, v121
	v_fma_f32 v14, v22, v18, v137
	v_fma_f32 v15, v23, v19, v153
	v_fmac_f32_dpp v12, v16, v24 quad_perm:[1,0,3,2] row_mask:0xf bank_mask:0xf
	v_fmac_f32_dpp v13, v17, v25 quad_perm:[1,0,3,2] row_mask:0xf bank_mask:0xf
	v_fmac_f32_dpp v14, v18, v26 quad_perm:[1,0,3,2] row_mask:0xf bank_mask:0xf
	v_fmac_f32_dpp v15, v19, v27 quad_perm:[1,0,3,2] row_mask:0xf bank_mask:0xf
	v_cvt_pk_f16_f32 v178, v16, v12
	v_cvt_pk_f16_f32 v182, v17, v13
	v_cvt_pk_f16_f32 v186, v18, v14
	v_cvt_pk_f16_f32 v190, v19, v15
	v_fma_f32 v16, v20, v12, v106
	v_fma_f32 v17, v21, v13, v122
	v_fma_f32 v18, v22, v14, v138
	v_fma_f32 v19, v23, v15, v154
	v_fmac_f32_dpp v16, v12, v24 quad_perm:[1,0,3,2] row_mask:0xf bank_mask:0xf
	v_fmac_f32_dpp v17, v13, v25 quad_perm:[1,0,3,2] row_mask:0xf bank_mask:0xf
	v_fmac_f32_dpp v18, v14, v26 quad_perm:[1,0,3,2] row_mask:0xf bank_mask:0xf
	v_fmac_f32_dpp v19, v15, v27 quad_perm:[1,0,3,2] row_mask:0xf bank_mask:0xf
	v_fma_f32 v12, v20, v16, v107
	v_fma_f32 v13, v21, v17, v123
	v_fma_f32 v14, v22, v18, v139
	v_fma_f32 v15, v23, v19, v155
	v_fmac_f32_dpp v12, v16, v24 quad_perm:[1,0,3,2] row_mask:0xf bank_mask:0xf
	v_fmac_f32_dpp v13, v17, v25 quad_perm:[1,0,3,2] row_mask:0xf bank_mask:0xf
	v_fmac_f32_dpp v14, v18, v26 quad_perm:[1,0,3,2] row_mask:0xf bank_mask:0xf
	v_fmac_f32_dpp v15, v19, v27 quad_perm:[1,0,3,2] row_mask:0xf bank_mask:0xf
	v_cvt_pk_f16_f32 v179, v16, v12
	v_cvt_pk_f16_f32 v183, v17, v13
	v_cvt_pk_f16_f32 v187, v18, v14
	v_cvt_pk_f16_f32 v191, v19, v15
	v_fma_f32 v16, v20, v12, v108
	v_fma_f32 v17, v21, v13, v124
	v_fma_f32 v18, v22, v14, v140
	v_fma_f32 v19, v23, v15, v156
	v_fmac_f32_dpp v16, v12, v24 quad_perm:[1,0,3,2] row_mask:0xf bank_mask:0xf
	v_fmac_f32_dpp v17, v13, v25 quad_perm:[1,0,3,2] row_mask:0xf bank_mask:0xf
	v_fmac_f32_dpp v18, v14, v26 quad_perm:[1,0,3,2] row_mask:0xf bank_mask:0xf
	v_fmac_f32_dpp v19, v15, v27 quad_perm:[1,0,3,2] row_mask:0xf bank_mask:0xf
	v_fma_f32 v12, v20, v16, v109
	v_fma_f32 v13, v21, v17, v125
	v_fma_f32 v14, v22, v18, v141
	v_fma_f32 v15, v23, v19, v157
	v_fmac_f32_dpp v12, v16, v24 quad_perm:[1,0,3,2] row_mask:0xf bank_mask:0xf
	v_fmac_f32_dpp v13, v17, v25 quad_perm:[1,0,3,2] row_mask:0xf bank_mask:0xf
	v_fmac_f32_dpp v14, v18, v26 quad_perm:[1,0,3,2] row_mask:0xf bank_mask:0xf
	v_fmac_f32_dpp v15, v19, v27 quad_perm:[1,0,3,2] row_mask:0xf bank_mask:0xf
	v_cvt_pk_f16_f32 v180, v16, v12
	v_cvt_pk_f16_f32 v184, v17, v13
	v_cvt_pk_f16_f32 v188, v18, v14
	v_cvt_pk_f16_f32 v192, v19, v15
	v_fma_f32 v16, v20, v12, v110
	v_fma_f32 v17, v21, v13, v126
	v_fma_f32 v18, v22, v14, v142
	v_fma_f32 v19, v23, v15, v158
	v_fmac_f32_dpp v16, v12, v24 quad_perm:[1,0,3,2] row_mask:0xf bank_mask:0xf
	v_fmac_f32_dpp v17, v13, v25 quad_perm:[1,0,3,2] row_mask:0xf bank_mask:0xf
	v_fmac_f32_dpp v18, v14, v26 quad_perm:[1,0,3,2] row_mask:0xf bank_mask:0xf
	v_fmac_f32_dpp v19, v15, v27 quad_perm:[1,0,3,2] row_mask:0xf bank_mask:0xf
	v_fma_f32 v12, v20, v16, v111
	v_fma_f32 v13, v21, v17, v127
	v_fma_f32 v14, v22, v18, v143
	v_fma_f32 v15, v23, v19, v159
	v_fmac_f32_dpp v12, v16, v24 quad_perm:[1,0,3,2] row_mask:0xf bank_mask:0xf
	v_fmac_f32_dpp v13, v17, v25 quad_perm:[1,0,3,2] row_mask:0xf bank_mask:0xf
	v_fmac_f32_dpp v14, v18, v26 quad_perm:[1,0,3,2] row_mask:0xf bank_mask:0xf
	v_fmac_f32_dpp v15, v19, v27 quad_perm:[1,0,3,2] row_mask:0xf bank_mask:0xf
	v_cvt_pk_f16_f32 v181, v16, v12
	v_cvt_pk_f16_f32 v185, v17, v13
	v_cvt_pk_f16_f32 v189, v18, v14
	v_cvt_pk_f16_f32 v193, v19, v15
	ds_write_b128 v84, v[178:181] offset:4160
	ds_write_b128 v84, v[182:185] offset:4672
	ds_write_b128 v84, v[186:189] offset:5184
	ds_write_b128 v84, v[190:193] offset:5696
	v_mfma_f32_32x32x16_f16 v[96:111], v[64:67], v[36:39], 0
	v_mfma_f32_32x32x16_f16 v[112:127], v[64:67], v[40:43], 0
	v_mfma_f32_32x32x16_f16 v[128:143], v[64:67], v[44:47], 0
	v_mfma_f32_32x32x16_f16 v[144:159], v[64:67], v[48:51], 0
	v_add_u32_e32 v93, s78, v87
	ds_read_b64_tr_b16 v[194:195], v85 offset:0
	ds_read_b64_tr_b16 v[196:197], v85 offset:64
	ds_read_b64_tr_b16 v[198:199], v85 offset:512
	ds_read_b64_tr_b16 v[200:201], v85 offset:576
	ds_read_b64_tr_b16 v[206:207], v85 offset:1024
	ds_read_b64_tr_b16 v[208:209], v85 offset:1088
	ds_read_b64_tr_b16 v[210:211], v85 offset:1536
	ds_read_b64_tr_b16 v[212:213], v85 offset:1600
	s_nop 3
	v_fma_f32 v16, v20, v12, v96
	v_fma_f32 v17, v21, v13, v112
	v_fma_f32 v18, v22, v14, v128
	v_fma_f32 v19, v23, v15, v144
	v_fmac_f32_dpp v16, v12, v24 quad_perm:[1,0,3,2] row_mask:0xf bank_mask:0xf
	v_fmac_f32_dpp v17, v13, v25 quad_perm:[1,0,3,2] row_mask:0xf bank_mask:0xf
	v_fmac_f32_dpp v18, v14, v26 quad_perm:[1,0,3,2] row_mask:0xf bank_mask:0xf
	v_fmac_f32_dpp v19, v15, v27 quad_perm:[1,0,3,2] row_mask:0xf bank_mask:0xf
	v_fma_f32 v12, v20, v16, v97
	v_fma_f32 v13, v21, v17, v113
	v_fma_f32 v14, v22, v18, v129
	v_fma_f32 v15, v23, v19, v145
	v_fmac_f32_dpp v12, v16, v24 quad_perm:[1,0,3,2] row_mask:0xf bank_mask:0xf
	v_fmac_f32_dpp v13, v17, v25 quad_perm:[1,0,3,2] row_mask:0xf bank_mask:0xf
	v_fmac_f32_dpp v14, v18, v26 quad_perm:[1,0,3,2] row_mask:0xf bank_mask:0xf
	v_fmac_f32_dpp v15, v19, v27 quad_perm:[1,0,3,2] row_mask:0xf bank_mask:0xf
	v_cvt_pk_f16_f32 v178, v16, v12
	v_cvt_pk_f16_f32 v182, v17, v13
	v_cvt_pk_f16_f32 v186, v18, v14
	v_cvt_pk_f16_f32 v190, v19, v15
	s_waitcnt lgkmcnt(6)
	v_mfma_f32_16x16x32_f16 v[32:35], v[160:163], v[194:197], 0
	s_waitcnt lgkmcnt(4)
	v_mfma_f32_16x16x32_f16 v[32:35], v[164:167], v[198:201], v[32:35]
	s_waitcnt lgkmcnt(2)
	v_mfma_f32_16x16x32_f16 v[32:35], v[168:171], v[206:209], v[32:35]
	s_waitcnt lgkmcnt(0)
	v_mfma_f32_16x16x32_f16 v[32:35], v[172:175], v[210:213], v[32:35]
	v_fma_f32 v16, v20, v12, v98
	v_fma_f32 v17, v21, v13, v114
	v_fma_f32 v18, v22, v14, v130
	v_fma_f32 v19, v23, v15, v146
	v_fmac_f32_dpp v16, v12, v24 quad_perm:[1,0,3,2] row_mask:0xf bank_mask:0xf
	v_fmac_f32_dpp v17, v13, v25 quad_perm:[1,0,3,2] row_mask:0xf bank_mask:0xf
	v_fmac_f32_dpp v18, v14, v26 quad_perm:[1,0,3,2] row_mask:0xf bank_mask:0xf
	v_fmac_f32_dpp v19, v15, v27 quad_perm:[1,0,3,2] row_mask:0xf bank_mask:0xf
	v_fma_f32 v12, v20, v16, v99
	v_fma_f32 v13, v21, v17, v115
	v_fma_f32 v14, v22, v18, v131
	v_fma_f32 v15, v23, v19, v147
	v_fmac_f32_dpp v12, v16, v24 quad_perm:[1,0,3,2] row_mask:0xf bank_mask:0xf
	v_fmac_f32_dpp v13, v17, v25 quad_perm:[1,0,3,2] row_mask:0xf bank_mask:0xf
	v_fmac_f32_dpp v14, v18, v26 quad_perm:[1,0,3,2] row_mask:0xf bank_mask:0xf
	v_fmac_f32_dpp v15, v19, v27 quad_perm:[1,0,3,2] row_mask:0xf bank_mask:0xf
	v_cvt_pk_f16_f32 v179, v16, v12
	v_cvt_pk_f16_f32 v183, v17, v13
	v_cvt_pk_f16_f32 v187, v18, v14
	v_cvt_pk_f16_f32 v191, v19, v15
	ds_write_b128 v93, v[32:35] offset:0
	ds_read_b64_tr_b16 v[194:195], v85 offset:2048
	ds_read_b64_tr_b16 v[196:197], v85 offset:2112
	ds_read_b64_tr_b16 v[198:199], v85 offset:2560
	ds_read_b64_tr_b16 v[200:201], v85 offset:2624
	ds_read_b64_tr_b16 v[206:207], v85 offset:3072
	ds_read_b64_tr_b16 v[208:209], v85 offset:3136
	ds_read_b64_tr_b16 v[210:211], v85 offset:3584
	ds_read_b64_tr_b16 v[212:213], v85 offset:3648
	v_fma_f32 v16, v20, v12, v100
	v_fma_f32 v17, v21, v13, v116
	v_fma_f32 v18, v22, v14, v132
	v_fma_f32 v19, v23, v15, v148
	v_fmac_f32_dpp v16, v12, v24 quad_perm:[1,0,3,2] row_mask:0xf bank_mask:0xf
	v_fmac_f32_dpp v17, v13, v25 quad_perm:[1,0,3,2] row_mask:0xf bank_mask:0xf
	v_fmac_f32_dpp v18, v14, v26 quad_perm:[1,0,3,2] row_mask:0xf bank_mask:0xf
	v_fmac_f32_dpp v19, v15, v27 quad_perm:[1,0,3,2] row_mask:0xf bank_mask:0xf
	v_fma_f32 v12, v20, v16, v101
	v_fma_f32 v13, v21, v17, v117
	v_fma_f32 v14, v22, v18, v133
	v_fma_f32 v15, v23, v19, v149
	v_fmac_f32_dpp v12, v16, v24 quad_perm:[1,0,3,2] row_mask:0xf bank_mask:0xf
	v_fmac_f32_dpp v13, v17, v25 quad_perm:[1,0,3,2] row_mask:0xf bank_mask:0xf
	v_fmac_f32_dpp v14, v18, v26 quad_perm:[1,0,3,2] row_mask:0xf bank_mask:0xf
	v_fmac_f32_dpp v15, v19, v27 quad_perm:[1,0,3,2] row_mask:0xf bank_mask:0xf
	v_cvt_pk_f16_f32 v180, v16, v12
	v_cvt_pk_f16_f32 v184, v17, v13
	v_cvt_pk_f16_f32 v188, v18, v14
	v_cvt_pk_f16_f32 v192, v19, v15
	s_waitcnt lgkmcnt(6)
	v_mfma_f32_16x16x32_f16 v[32:35], v[160:163], v[194:197], 0
	s_waitcnt lgkmcnt(4)
	v_mfma_f32_16x16x32_f16 v[32:35], v[164:167], v[198:201], v[32:35]
	s_waitcnt lgkmcnt(2)
	v_mfma_f32_16x16x32_f16 v[32:35], v[168:171], v[206:209], v[32:35]
	s_waitcnt lgkmcnt(0)
	v_mfma_f32_16x16x32_f16 v[32:35], v[172:175], v[210:213], v[32:35]
	v_fma_f32 v16, v20, v12, v102
	v_fma_f32 v17, v21, v13, v118
	v_fma_f32 v18, v22, v14, v134
	v_fma_f32 v19, v23, v15, v150
	v_fmac_f32_dpp v16, v12, v24 quad_perm:[1,0,3,2] row_mask:0xf bank_mask:0xf
	v_fmac_f32_dpp v17, v13, v25 quad_perm:[1,0,3,2] row_mask:0xf bank_mask:0xf
	v_fmac_f32_dpp v18, v14, v26 quad_perm:[1,0,3,2] row_mask:0xf bank_mask:0xf
	v_fmac_f32_dpp v19, v15, v27 quad_perm:[1,0,3,2] row_mask:0xf bank_mask:0xf
	v_fma_f32 v12, v20, v16, v103
	v_fma_f32 v13, v21, v17, v119
	v_fma_f32 v14, v22, v18, v135
	v_fma_f32 v15, v23, v19, v151
	v_fmac_f32_dpp v12, v16, v24 quad_perm:[1,0,3,2] row_mask:0xf bank_mask:0xf
	v_fmac_f32_dpp v13, v17, v25 quad_perm:[1,0,3,2] row_mask:0xf bank_mask:0xf
	v_fmac_f32_dpp v14, v18, v26 quad_perm:[1,0,3,2] row_mask:0xf bank_mask:0xf
	v_fmac_f32_dpp v15, v19, v27 quad_perm:[1,0,3,2] row_mask:0xf bank_mask:0xf
	v_cvt_pk_f16_f32 v181, v16, v12
	v_cvt_pk_f16_f32 v185, v17, v13
	v_cvt_pk_f16_f32 v189, v18, v14
	v_cvt_pk_f16_f32 v193, v19, v15
	ds_write_b128 v84, v[178:181] offset:0
	ds_write_b128 v84, v[182:185] offset:512
	ds_write_b128 v84, v[186:189] offset:1024
	ds_write_b128 v84, v[190:193] offset:1536
	v_fma_f32 v16, v20, v12, v104
	v_fma_f32 v17, v21, v13, v120
	v_fma_f32 v18, v22, v14, v136
	v_fma_f32 v19, v23, v15, v152
	v_fmac_f32_dpp v16, v12, v24 quad_perm:[1,0,3,2] row_mask:0xf bank_mask:0xf
	v_fmac_f32_dpp v17, v13, v25 quad_perm:[1,0,3,2] row_mask:0xf bank_mask:0xf
	v_fmac_f32_dpp v18, v14, v26 quad_perm:[1,0,3,2] row_mask:0xf bank_mask:0xf
	v_fmac_f32_dpp v19, v15, v27 quad_perm:[1,0,3,2] row_mask:0xf bank_mask:0xf
	ds_write_b128 v93, v[32:35] offset:4096
	v_fma_f32 v12, v20, v16, v105
	v_fma_f32 v13, v21, v17, v121
	v_fma_f32 v14, v22, v18, v137
	v_fma_f32 v15, v23, v19, v153
	v_fmac_f32_dpp v12, v16, v24 quad_perm:[1,0,3,2] row_mask:0xf bank_mask:0xf
	v_fmac_f32_dpp v13, v17, v25 quad_perm:[1,0,3,2] row_mask:0xf bank_mask:0xf
	v_fmac_f32_dpp v14, v18, v26 quad_perm:[1,0,3,2] row_mask:0xf bank_mask:0xf
	v_fmac_f32_dpp v15, v19, v27 quad_perm:[1,0,3,2] row_mask:0xf bank_mask:0xf
	v_cvt_pk_f16_f32 v178, v16, v12
	v_cvt_pk_f16_f32 v182, v17, v13
	v_cvt_pk_f16_f32 v186, v18, v14
	v_cvt_pk_f16_f32 v190, v19, v15
	v_fma_f32 v16, v20, v12, v106
	v_fma_f32 v17, v21, v13, v122
	v_fma_f32 v18, v22, v14, v138
	v_fma_f32 v19, v23, v15, v154
	v_fmac_f32_dpp v16, v12, v24 quad_perm:[1,0,3,2] row_mask:0xf bank_mask:0xf
	v_fmac_f32_dpp v17, v13, v25 quad_perm:[1,0,3,2] row_mask:0xf bank_mask:0xf
	v_fmac_f32_dpp v18, v14, v26 quad_perm:[1,0,3,2] row_mask:0xf bank_mask:0xf
	v_fmac_f32_dpp v19, v15, v27 quad_perm:[1,0,3,2] row_mask:0xf bank_mask:0xf
	v_fma_f32 v12, v20, v16, v107
	v_fma_f32 v13, v21, v17, v123
	v_fma_f32 v14, v22, v18, v139
	v_fma_f32 v15, v23, v19, v155
	v_fmac_f32_dpp v12, v16, v24 quad_perm:[1,0,3,2] row_mask:0xf bank_mask:0xf
	v_fmac_f32_dpp v13, v17, v25 quad_perm:[1,0,3,2] row_mask:0xf bank_mask:0xf
	v_fmac_f32_dpp v14, v18, v26 quad_perm:[1,0,3,2] row_mask:0xf bank_mask:0xf
	v_fmac_f32_dpp v15, v19, v27 quad_perm:[1,0,3,2] row_mask:0xf bank_mask:0xf
	v_cvt_pk_f16_f32 v179, v16, v12
	v_cvt_pk_f16_f32 v183, v17, v13
	v_cvt_pk_f16_f32 v187, v18, v14
	v_cvt_pk_f16_f32 v191, v19, v15
	v_fma_f32 v16, v20, v12, v108
	v_fma_f32 v17, v21, v13, v124
	v_fma_f32 v18, v22, v14, v140
	v_fma_f32 v19, v23, v15, v156
	v_fmac_f32_dpp v16, v12, v24 quad_perm:[1,0,3,2] row_mask:0xf bank_mask:0xf
	v_fmac_f32_dpp v17, v13, v25 quad_perm:[1,0,3,2] row_mask:0xf bank_mask:0xf
	v_fmac_f32_dpp v18, v14, v26 quad_perm:[1,0,3,2] row_mask:0xf bank_mask:0xf
	v_fmac_f32_dpp v19, v15, v27 quad_perm:[1,0,3,2] row_mask:0xf bank_mask:0xf
	v_fma_f32 v12, v20, v16, v109
	v_fma_f32 v13, v21, v17, v125
	v_fma_f32 v14, v22, v18, v141
	v_fma_f32 v15, v23, v19, v157
	v_fmac_f32_dpp v12, v16, v24 quad_perm:[1,0,3,2] row_mask:0xf bank_mask:0xf
	v_fmac_f32_dpp v13, v17, v25 quad_perm:[1,0,3,2] row_mask:0xf bank_mask:0xf
	v_fmac_f32_dpp v14, v18, v26 quad_perm:[1,0,3,2] row_mask:0xf bank_mask:0xf
	v_fmac_f32_dpp v15, v19, v27 quad_perm:[1,0,3,2] row_mask:0xf bank_mask:0xf
	v_cvt_pk_f16_f32 v180, v16, v12
	v_cvt_pk_f16_f32 v184, v17, v13
	v_cvt_pk_f16_f32 v188, v18, v14
	v_cvt_pk_f16_f32 v192, v19, v15
	v_fma_f32 v16, v20, v12, v110
	v_fma_f32 v17, v21, v13, v126
	v_fma_f32 v18, v22, v14, v142
	v_fma_f32 v19, v23, v15, v158
	v_fmac_f32_dpp v16, v12, v24 quad_perm:[1,0,3,2] row_mask:0xf bank_mask:0xf
	v_fmac_f32_dpp v17, v13, v25 quad_perm:[1,0,3,2] row_mask:0xf bank_mask:0xf
	v_fmac_f32_dpp v18, v14, v26 quad_perm:[1,0,3,2] row_mask:0xf bank_mask:0xf
	v_fmac_f32_dpp v19, v15, v27 quad_perm:[1,0,3,2] row_mask:0xf bank_mask:0xf
	v_fma_f32 v12, v20, v16, v111
	v_fma_f32 v13, v21, v17, v127
	v_fma_f32 v14, v22, v18, v143
	v_fma_f32 v15, v23, v19, v159
	v_fmac_f32_dpp v12, v16, v24 quad_perm:[1,0,3,2] row_mask:0xf bank_mask:0xf
	v_fmac_f32_dpp v13, v17, v25 quad_perm:[1,0,3,2] row_mask:0xf bank_mask:0xf
	v_fmac_f32_dpp v14, v18, v26 quad_perm:[1,0,3,2] row_mask:0xf bank_mask:0xf
	v_fmac_f32_dpp v15, v19, v27 quad_perm:[1,0,3,2] row_mask:0xf bank_mask:0xf
	v_cvt_pk_f16_f32 v181, v16, v12
	v_cvt_pk_f16_f32 v185, v17, v13
	v_cvt_pk_f16_f32 v189, v18, v14
	v_cvt_pk_f16_f32 v193, v19, v15
	ds_write_b128 v84, v[178:181] offset:4160
	ds_write_b128 v84, v[182:185] offset:4672
	ds_write_b128 v84, v[186:189] offset:5184
	ds_write_b128 v84, v[190:193] offset:5696
	v_add_u32_e32 v93, s79, v87
	ds_read_b64_tr_b16 v[194:195], v85 offset:0
	ds_read_b64_tr_b16 v[196:197], v85 offset:64
	ds_read_b64_tr_b16 v[198:199], v85 offset:512
	ds_read_b64_tr_b16 v[200:201], v85 offset:576
	ds_read_b64_tr_b16 v[206:207], v85 offset:1024
	ds_read_b64_tr_b16 v[208:209], v85 offset:1088
	ds_read_b64_tr_b16 v[210:211], v85 offset:1536
	ds_read_b64_tr_b16 v[212:213], v85 offset:1600
	s_waitcnt lgkmcnt(6)
	v_mfma_f32_16x16x32_f16 v[32:35], v[160:163], v[194:197], 0
	s_waitcnt lgkmcnt(4)
	v_mfma_f32_16x16x32_f16 v[32:35], v[164:167], v[198:201], v[32:35]
	s_waitcnt lgkmcnt(2)
	v_mfma_f32_16x16x32_f16 v[32:35], v[168:171], v[206:209], v[32:35]
	s_waitcnt lgkmcnt(0)
	v_mfma_f32_16x16x32_f16 v[32:35], v[172:175], v[210:213], v[32:35]
	s_nop 7
	s_nop 1
	ds_write_b128 v93, v[32:35] offset:0
	ds_read_b64_tr_b16 v[194:195], v85 offset:2048
	ds_read_b64_tr_b16 v[196:197], v85 offset:2112
	ds_read_b64_tr_b16 v[198:199], v85 offset:2560
	ds_read_b64_tr_b16 v[200:201], v85 offset:2624
	ds_read_b64_tr_b16 v[206:207], v85 offset:3072
	ds_read_b64_tr_b16 v[208:209], v85 offset:3136
	ds_read_b64_tr_b16 v[210:211], v85 offset:3584
	ds_read_b64_tr_b16 v[212:213], v85 offset:3648
	s_waitcnt lgkmcnt(6)
	v_mfma_f32_16x16x32_f16 v[32:35], v[160:163], v[194:197], 0
	s_waitcnt lgkmcnt(4)
	v_mfma_f32_16x16x32_f16 v[32:35], v[164:167], v[198:201], v[32:35]
	s_waitcnt lgkmcnt(2)
	v_mfma_f32_16x16x32_f16 v[32:35], v[168:171], v[206:209], v[32:35]
	s_waitcnt lgkmcnt(0)
	v_mfma_f32_16x16x32_f16 v[32:35], v[172:175], v[210:213], v[32:35]
	s_nop 7
	s_nop 1
	ds_write_b128 v93, v[32:35] offset:4096
	s_waitcnt vmcnt(0) lgkmcnt(0)
	s_barrier
	ds_read_b128 v[96:99], v88 offset:0
	ds_read_b128 v[100:103], v88 offset:16
	ds_read_b128 v[104:107], v88 offset:8192
	ds_read_b128 v[108:111], v88 offset:8208
	ds_read_b128 v[112:115], v88 offset:4096
	ds_read_b128 v[116:119], v88 offset:4112
	ds_read_b128 v[120:123], v88 offset:12288
	ds_read_b128 v[124:127], v88 offset:12304
	s_waitcnt lgkmcnt(4)
	v_add_f32_e32 v128, v96, v104
	v_add_f32_e32 v129, v97, v105
	v_add_f32_e32 v130, v98, v106
	v_add_f32_e32 v131, v99, v107
	v_add_f32_e32 v132, v100, v108
	v_add_f32_e32 v133, v101, v109
	v_add_f32_e32 v134, v102, v110
	v_add_f32_e32 v135, v103, v111
	v_cvt_f32_f16_e32 v144, v214
	v_cvt_f32_f16_sdwa v145, v214 dst_sel:DWORD dst_unused:UNUSED_PAD src0_sel:WORD_1
	v_cvt_f32_f16_e32 v146, v215
	v_cvt_f32_f16_sdwa v147, v215 dst_sel:DWORD dst_unused:UNUSED_PAD src0_sel:WORD_1
	v_cvt_f32_f16_e32 v148, v216
	v_cvt_f32_f16_sdwa v149, v216 dst_sel:DWORD dst_unused:UNUSED_PAD src0_sel:WORD_1
	v_cvt_f32_f16_e32 v150, v217
	v_cvt_f32_f16_sdwa v151, v217 dst_sel:DWORD dst_unused:UNUSED_PAD src0_sel:WORD_1
	v_mul_f32_e32 v144, v144, v222
	v_mul_f32_e32 v145, v145, v223
	v_mul_f32_e32 v146, v146, v224
	v_mul_f32_e32 v147, v147, v225
	v_mul_f32_e32 v148, v148, v226
	v_mul_f32_e32 v149, v149, v227
	v_mul_f32_e32 v150, v150, v228
	v_mul_f32_e32 v151, v151, v229
	v_fma_f32 v136, v128, s81, v144
	v_fma_f32 v137, v129, s81, v145
	v_fma_f32 v138, v130, s81, v146
	v_fma_f32 v139, v131, s81, v147
	v_fma_f32 v140, v132, s81, v148
	v_fma_f32 v141, v133, s81, v149
	v_fma_f32 v142, v134, s81, v150
	v_fma_f32 v143, v135, s81, v151
	v_mul_f32_e32 v144, v136, v136
	v_mul_f32_e32 v145, v137, v137
	v_mul_f32_e32 v146, v138, v138
	v_mul_f32_e32 v147, v139, v139
	v_mul_f32_e32 v148, v140, v140
	v_mul_f32_e32 v149, v141, v141
	v_mul_f32_e32 v150, v142, v142
	v_mul_f32_e32 v151, v143, v143
	v_mul_f32_e32 v144, v144, v136
	v_mul_f32_e32 v145, v145, v137
	v_mul_f32_e32 v146, v146, v138
	v_mul_f32_e32 v147, v147, v139
	v_mul_f32_e32 v148, v148, v140
	v_mul_f32_e32 v149, v149, v141
	v_mul_f32_e32 v150, v150, v142
	v_mul_f32_e32 v151, v151, v143
	v_fma_f32 v144, v144, s82, v136
	v_fma_f32 v145, v145, s82, v137
	v_fma_f32 v146, v146, s82, v138
	v_fma_f32 v147, v147, s82, v139
	v_fma_f32 v148, v148, s82, v140
	v_fma_f32 v149, v149, s82, v141
	v_fma_f32 v150, v150, s82, v142
	v_fma_f32 v151, v151, s82, v143
	v_mul_f32_e32 v144, 0xc0135761, v144
	v_mul_f32_e32 v145, 0xc0135761, v145
	v_mul_f32_e32 v146, 0xc0135761, v146
	v_mul_f32_e32 v147, 0xc0135761, v147
	v_mul_f32_e32 v148, 0xc0135761, v148
	v_mul_f32_e32 v149, 0xc0135761, v149
	v_mul_f32_e32 v150, 0xc0135761, v150
	v_mul_f32_e32 v151, 0xc0135761, v151
	v_exp_f32_e32 v144, v144
	v_exp_f32_e32 v145, v145
	v_exp_f32_e32 v146, v146
	v_exp_f32_e32 v147, v147
	v_exp_f32_e32 v148, v148
	v_exp_f32_e32 v149, v149
	v_exp_f32_e32 v150, v150
	v_exp_f32_e32 v151, v151
	v_add_f32_e32 v144, 1.0, v144
	v_add_f32_e32 v145, 1.0, v145
	v_add_f32_e32 v146, 1.0, v146
	v_add_f32_e32 v147, 1.0, v147
	v_add_f32_e32 v148, 1.0, v148
	v_add_f32_e32 v149, 1.0, v149
	v_add_f32_e32 v150, 1.0, v150
	v_add_f32_e32 v151, 1.0, v151
	v_rcp_f32_e32 v144, v144
	v_rcp_f32_e32 v145, v145
	v_rcp_f32_e32 v146, v146
	v_rcp_f32_e32 v147, v147
	v_rcp_f32_e32 v148, v148
	v_rcp_f32_e32 v149, v149
	v_rcp_f32_e32 v150, v150
	v_rcp_f32_e32 v151, v151
	v_mul_f32_e32 v136, v136, v144
	v_mul_f32_e32 v137, v137, v145
	v_mul_f32_e32 v138, v138, v146
	v_mul_f32_e32 v139, v139, v147
	v_mul_f32_e32 v140, v140, v148
	v_mul_f32_e32 v141, v141, v149
	v_mul_f32_e32 v142, v142, v150
	v_mul_f32_e32 v143, v143, v151
	v_cvt_pk_f16_f32 v152, v136, v137
	v_cvt_pk_f16_f32 v153, v138, v139
	v_cvt_pk_f16_f32 v154, v140, v141
	v_cvt_pk_f16_f32 v155, v142, v143
	global_store_dwordx4 v91, v[152:155], s[74:75]
	s_nop 1
	s_waitcnt lgkmcnt(0)
	v_add_f32_e32 v128, v112, v120
	v_add_f32_e32 v129, v113, v121
	v_add_f32_e32 v130, v114, v122
	v_add_f32_e32 v131, v115, v123
	v_add_f32_e32 v132, v116, v124
	v_add_f32_e32 v133, v117, v125
	v_add_f32_e32 v134, v118, v126
	v_add_f32_e32 v135, v119, v127
	v_cvt_f32_f16_e32 v144, v218
	v_cvt_f32_f16_sdwa v145, v218 dst_sel:DWORD dst_unused:UNUSED_PAD src0_sel:WORD_1
	v_cvt_f32_f16_e32 v146, v219
	v_cvt_f32_f16_sdwa v147, v219 dst_sel:DWORD dst_unused:UNUSED_PAD src0_sel:WORD_1
	v_cvt_f32_f16_e32 v148, v220
	v_cvt_f32_f16_sdwa v149, v220 dst_sel:DWORD dst_unused:UNUSED_PAD src0_sel:WORD_1
	v_cvt_f32_f16_e32 v150, v221
	v_cvt_f32_f16_sdwa v151, v221 dst_sel:DWORD dst_unused:UNUSED_PAD src0_sel:WORD_1
	v_mul_f32_e32 v144, v144, v222
	v_mul_f32_e32 v145, v145, v223
	v_mul_f32_e32 v146, v146, v224
	v_mul_f32_e32 v147, v147, v225
	v_mul_f32_e32 v148, v148, v226
	v_mul_f32_e32 v149, v149, v227
	v_mul_f32_e32 v150, v150, v228
	v_mul_f32_e32 v151, v151, v229
	v_fma_f32 v136, v128, s81, v144
	v_fma_f32 v137, v129, s81, v145
	v_fma_f32 v138, v130, s81, v146
	v_fma_f32 v139, v131, s81, v147
	v_fma_f32 v140, v132, s81, v148
	v_fma_f32 v141, v133, s81, v149
	v_fma_f32 v142, v134, s81, v150
	v_fma_f32 v143, v135, s81, v151
	v_mul_f32_e32 v144, v136, v136
	v_mul_f32_e32 v145, v137, v137
	v_mul_f32_e32 v146, v138, v138
	v_mul_f32_e32 v147, v139, v139
	v_mul_f32_e32 v148, v140, v140
	v_mul_f32_e32 v149, v141, v141
	v_mul_f32_e32 v150, v142, v142
	v_mul_f32_e32 v151, v143, v143
	v_mul_f32_e32 v144, v144, v136
	v_mul_f32_e32 v145, v145, v137
	v_mul_f32_e32 v146, v146, v138
	v_mul_f32_e32 v147, v147, v139
	v_mul_f32_e32 v148, v148, v140
	v_mul_f32_e32 v149, v149, v141
	v_mul_f32_e32 v150, v150, v142
	v_mul_f32_e32 v151, v151, v143
	v_fma_f32 v144, v144, s82, v136
	v_fma_f32 v145, v145, s82, v137
	v_fma_f32 v146, v146, s82, v138
	v_fma_f32 v147, v147, s82, v139
	v_fma_f32 v148, v148, s82, v140
	v_fma_f32 v149, v149, s82, v141
	v_fma_f32 v150, v150, s82, v142
	v_fma_f32 v151, v151, s82, v143
	v_mul_f32_e32 v144, 0xc0135761, v144
	v_mul_f32_e32 v145, 0xc0135761, v145
	v_mul_f32_e32 v146, 0xc0135761, v146
	v_mul_f32_e32 v147, 0xc0135761, v147
	v_mul_f32_e32 v148, 0xc0135761, v148
	v_mul_f32_e32 v149, 0xc0135761, v149
	v_mul_f32_e32 v150, 0xc0135761, v150
	v_mul_f32_e32 v151, 0xc0135761, v151
	v_exp_f32_e32 v144, v144
	v_exp_f32_e32 v145, v145
	v_exp_f32_e32 v146, v146
	v_exp_f32_e32 v147, v147
	v_exp_f32_e32 v148, v148
	v_exp_f32_e32 v149, v149
	v_exp_f32_e32 v150, v150
	v_exp_f32_e32 v151, v151
	v_add_f32_e32 v144, 1.0, v144
	v_add_f32_e32 v145, 1.0, v145
	v_add_f32_e32 v146, 1.0, v146
	v_add_f32_e32 v147, 1.0, v147
	v_add_f32_e32 v148, 1.0, v148
	v_add_f32_e32 v149, 1.0, v149
	v_add_f32_e32 v150, 1.0, v150
	v_add_f32_e32 v151, 1.0, v151
	v_rcp_f32_e32 v144, v144
	v_rcp_f32_e32 v145, v145
	v_rcp_f32_e32 v146, v146
	v_rcp_f32_e32 v147, v147
	v_rcp_f32_e32 v148, v148
	v_rcp_f32_e32 v149, v149
	v_rcp_f32_e32 v150, v150
	v_rcp_f32_e32 v151, v151
	v_mul_f32_e32 v136, v136, v144
	v_mul_f32_e32 v137, v137, v145
	v_mul_f32_e32 v138, v138, v146
	v_mul_f32_e32 v139, v139, v147
	v_mul_f32_e32 v140, v140, v148
	v_mul_f32_e32 v141, v141, v149
	v_mul_f32_e32 v142, v142, v150
	v_mul_f32_e32 v143, v143, v151
	v_cvt_pk_f16_f32 v152, v136, v137
	v_cvt_pk_f16_f32 v153, v138, v139
	v_cvt_pk_f16_f32 v154, v140, v141
	v_cvt_pk_f16_f32 v155, v142, v143
	global_store_dwordx4 v92, v[152:155], s[74:75]
	s_nop 1
	s_barrier
	s_cmpk_gt_u32 s5, 0x83f
	s_cbranch_scc0 .Lp8_top
.Lp8_done:
.LBB0_659:
	s_cmp_gt_i32 s91, 9
	s_cselect_b64 s[2:3], -1, 0
	s_and_b64 s[0:1], s[0:1], s[2:3]
	s_andn2_b64 vcc, exec, s[0:1]
	s_cbranch_vccnz .LBB0_713
	s_waitcnt vmcnt(0)
	s_waitcnt lgkmcnt(0)
	s_barrier
	s_and_saveexec_b64 s[0:1], s[92:93]
	s_cbranch_execz .LBB0_712
	s_add_i32 s4, 0, 0x27ff0
	v_mov_b32_e32 v0, s4
	s_waitcnt vmcnt(0) expcnt(0) lgkmcnt(0)
	ds_read_b32 v2, v0
	s_add_i32 s4, 0, 0x27ff4
	v_mov_b32_e32 v0, s4
	ds_read_b32 v0, v0
	s_waitcnt lgkmcnt(1)
	v_cmp_ne_u32_e32 vcc, 0, v2
	s_cbranch_vccnz .LBB0_676
	s_add_u32 s4, s30, 0x38200
	s_addc_u32 s5, s31, 0
	s_add_u32 s6, s30, 0x38400
	s_addc_u32 s7, s31, 0
	s_add_u32 s10, s30, 0x38500
	s_addc_u32 s11, s31, 0
	s_add_u32 s12, s30, 0x38600
	s_addc_u32 s13, s31, 0
	s_add_u32 s14, s30, 0x38700
	s_addc_u32 s15, s31, 0
	s_add_u32 s16, s30, 0x38800
	s_addc_u32 s17, s31, 0
	s_add_u32 s18, s30, 0x38900
	s_addc_u32 s19, s31, 0
	s_add_u32 s20, s30, 0x38a00
	s_addc_u32 s21, s31, 0
	s_add_u32 s22, s30, 0x38b00
	s_addc_u32 s23, s31, 0
	s_add_u32 s24, s30, 0x38c00
	s_addc_u32 s25, s31, 0
	s_add_u32 s26, s30, 0x38d00
	s_addc_u32 s27, s31, 0
	s_add_u32 s34, s30, 0x38e00
	s_addc_u32 s35, s31, 0
	s_add_u32 s40, s30, 0x38f00
	s_addc_u32 s41, s31, 0
	s_add_u32 s44, s30, 0x39000
	s_addc_u32 s45, s31, 0
	s_add_u32 s46, s30, 0x39100
	s_addc_u32 s47, s31, 0
	s_add_u32 s48, s30, 0x39200
	s_addc_u32 s49, s31, 0
	s_mul_i32 s33, s89, s9
	s_add_u32 s54, s30, 0x39300
	s_mul_i32 s33, s33, s88
	s_addc_u32 s55, s31, 0
	s_mov_b32 s62, 1
	v_mov_b32_e32 v16, 0
	s_branch .LBB0_664
